# split barrier: the arrival of prep-only workgroups is done by wave 7 (no per-half decay work in its conv stage) instead of wave 0
# speedup vs baseline: 1.0023x; 1.0023x over previous
.LBB0_752:
	s_cmpk_lt_i32 s10, 0x3e8
	s_cbranch_scc0 .LBB0_806
	s_waitcnt vmcnt(0)
	s_waitcnt lgkmcnt(0)
	s_barrier
	s_cmp_eq_u32 s10, 4
	s_cbranch_scc1 .Ltramp_b45
	s_mov_b64 s[0:1], exec
	v_readlane_b32 s16, v250, 3
	v_readlane_b32 s17, v250, 4
	v_readlane_b32 s22, v250, 0
	v_readlane_b32 s23, v254, 38
	s_nop 3
	s_cmp_lt_u32 s22, 0x80
	s_cbranch_scc1 .Lsb_t0
	s_cmp_lt_u32 s23, 6
	s_cbranch_scc1 .Lsb_t0
	s_cmp_gt_u32 s23, 12
	s_cbranch_scc1 .Lsb_t0
	v_mov_b32_e32 v0, 0x1c0
	v_cmp_eq_u32_e64 s[16:17], v228, v0
	s_nop 1
.Lsb_t0:
	s_and_b64 s[16:17], s[0:1], s[16:17]
	s_mov_b64 exec, s[16:17]
	s_cbranch_execz .LBB0_805
	v_readlane_b32 s2, v254, 20
	s_waitcnt vmcnt(0) expcnt(0) lgkmcnt(0)
	s_nop 0
	v_mov_b32_e32 v0, s2
	ds_read_b32 v3, v0
	v_readlane_b32 s2, v254, 21
	s_waitcnt lgkmcnt(0)
	v_cmp_ne_u32_e32 vcc, 0, v3
	v_mov_b32_e32 v0, s2
	ds_read_b32 v2, v0
	s_cbranch_vccnz .LBB0_769
	s_mov_b32 s2, 1
	s_branch .LBB0_757
